# G2/G4 main residual epilogues: second 128-row half's y loads issued with the first half's (counted vmcnt); on top of G1 order tables + LN prefetch
# speedup vs baseline: 1.0060x; 1.0003x over previous
.LBB0_903:
	s_ashr_i32 s17, s20, 4
	s_mul_i32 s22, s17, 6
	v_mov_b32_e32 v130, v199
	v_mov_b32_e32 v131, v65
	s_ashr_i32 s23, s22, 31
	s_lshl_b64 s[22:23], s[22:23], 13
	v_add_u32_e32 v228, s73, v130
	v_lshl_add_u32 v130, s20, 8, v228
	s_add_u32 s54, s69, s22
	v_lshlrev_b32_e32 v229, 3, v131
	s_addc_u32 s55, s70, s23
	s_and_b64 vcc, exec, s[88:89]
	v_lshlrev_b32_e32 v227, 12, v130
	s_cbranch_vccz .LBB0_909
	v_lshlrev_b32_e32 v130, 3, v130
	v_add_u32_e32 v131, 0x80, v130
	global_load_dwordx2 v[196:197], v130, s[56:57]
	global_load_dwordx2 v[194:195], v131, s[56:57]
	v_add_u32_e32 v131, 0x100, v130
	global_load_dwordx2 v[192:193], v131, s[56:57]
	v_add_u32_e32 v131, 0x180, v130
	s_lshl_b32 s17, s86, 8
	global_load_dwordx2 v[190:191], v131, s[56:57]
	v_add_u32_e32 v131, 0x400, v130
	s_or_b32 s17, s17, s80
	global_load_dwordx2 v[188:189], v131, s[56:57]
	v_add_u32_e32 v131, 0x480, v130
	v_add_u32_e32 v230, s17, v229
	global_load_dwordx2 v[186:187], v131, s[56:57]
	v_add_u32_e32 v131, 0x500, v130
	v_add_u32_e32 v130, 0x580, v130
	v_lshlrev_b32_e32 v150, 2, v230
	global_load_dwordx2 v[184:185], v131, s[56:57]
	global_load_dwordx2 v[182:183], v130, s[56:57]
	s_nop 0
	global_load_dwordx4 v[130:133], v150, s[54:55] offset:16
	global_load_dwordx4 v[138:141], v150, s[54:55]
	global_load_dwordx4 v[134:137], v150, s[38:39] offset:16
	global_load_dwordx4 v[142:145], v150, s[38:39]
	global_load_dwordx4 v[146:149], v150, s[0:1] offset:16
	s_nop 0
	global_load_dwordx4 v[150:153], v150, s[0:1]
	v_lshl_add_u32 v231, v230, 1, v227
	global_load_dwordx4 v[162:165], v231, s[42:43]
	v_add_u32_e32 v234, 0x10000, v231
	v_add_u32_e32 v233, 0x20000, v231
	v_add_u32_e32 v232, 0x30000, v231
	global_load_dwordx4 v[154:157], v234, s[42:43]
	s_waitcnt vmcnt(0)
	v_mul_f32_e32 v198, 0x3fd744fd, v197
	v_pk_mul_f32 v[200:201], v[148:149], s[76:77] op_sel_hi:[1,0]
	v_pk_mul_f32 v[204:205], v[152:153], s[76:77] op_sel_hi:[1,0]
	v_pk_mul_f32 v[206:207], v[150:151], s[76:77] op_sel_hi:[1,0]
	v_pk_mul_f32 v[202:203], v[146:147], s[76:77] op_sel_hi:[1,0]
	global_load_dwordx4 v[150:153], v233, s[42:43]
	global_load_dwordx4 v[146:149], v232, s[42:43]
	v_add_u32_e32 v158, 0x80000, v231
	global_load_dwordx4 v[174:177], v158, s[42:43]
	v_add_u32_e32 v158, 0x90000, v231
	global_load_dwordx4 v[178:181], v158, s[42:43]
	v_add_u32_e32 v158, 0xa0000, v231
	global_load_dwordx4 v[240:243], v158, s[42:43]
	v_add_u32_e32 v158, 0xb0000, v231
	global_load_dwordx4 v[244:247], v158, s[42:43]
	s_waitcnt vmcnt(5)
	s_waitcnt vmcnt(4)
	v_lshlrev_b32_e32 v170, 16, v162
	v_and_b32_e32 v162, 0xffff0000, v162
	v_lshlrev_b32_e32 v171, 16, v163
	v_and_b32_e32 v172, 0xffff0000, v163
	v_sub_f32_e32 v163, v162, v196
	v_sub_f32_e32 v162, v170, v196
	v_lshlrev_b32_e32 v173, 16, v164
	v_and_b32_e32 v197, 0xffff0000, v164
	v_lshlrev_b32_e32 v208, 16, v165
	v_and_b32_e32 v235, 0xffff0000, v165
	v_sub_f32_e32 v165, v172, v196
	v_sub_f32_e32 v164, v171, v196
	v_pk_mul_f32 v[162:163], v[198:199], v[162:163] op_sel_hi:[0,1]
	v_pk_mul_f32 v[164:165], v[198:199], v[164:165] op_sel_hi:[0,1]
	v_pk_fma_f32 v[162:163], v[142:143], v[162:163], v[206:207]
	v_sub_f32_e32 v171, v197, v196
	v_sub_f32_e32 v170, v173, v196
	v_sub_f32_e32 v173, v235, v196
	v_sub_f32_e32 v172, v208, v196
	v_pk_fma_f32 v[164:165], v[144:145], v[164:165], v[204:205]
	v_pk_fma_f32 v[162:163], v[126:127], v[138:139], v[162:163]
	v_pk_mul_f32 v[172:173], v[198:199], v[172:173] op_sel_hi:[0,1]
	v_pk_mul_f32 v[170:171], v[198:199], v[170:171] op_sel_hi:[0,1]
	v_pk_fma_f32 v[164:165], v[128:129], v[140:141], v[164:165]
	v_pk_fma_f32 v[170:171], v[134:135], v[170:171], v[202:203]
	v_pk_fma_f32 v[172:173], v[136:137], v[172:173], v[200:201]
	v_cvt_pk_bf16_f32 v162, v162, v163
	v_pk_fma_f32 v[170:171], v[122:123], v[130:131], v[170:171]
	v_pk_fma_f32 v[172:173], v[124:125], v[132:133], v[172:173]
	v_cvt_pk_bf16_f32 v163, v164, v165
	v_cvt_pk_bf16_f32 v164, v170, v171
	v_mul_f32_e32 v208, 0x3fd744fd, v195
	v_cvt_pk_bf16_f32 v165, v172, v173
	global_store_dwordx4 v231, v[162:165], s[46:47]
	v_and_b32_e32 v170, 0xffff0000, v156
	v_lshlrev_b32_e32 v171, 16, v157
	v_lshlrev_b32_e32 v162, 16, v154
	v_and_b32_e32 v154, 0xffff0000, v154
	v_lshlrev_b32_e32 v163, 16, v155
	v_and_b32_e32 v164, 0xffff0000, v155
	v_sub_f32_e32 v155, v154, v194
	v_sub_f32_e32 v154, v162, v194
	v_lshlrev_b32_e32 v165, 16, v156
	v_and_b32_e32 v172, 0xffff0000, v157
	v_sub_f32_e32 v157, v164, v194
	v_sub_f32_e32 v156, v163, v194
	v_pk_mul_f32 v[154:155], v[208:209], v[154:155] op_sel_hi:[0,1]
	v_pk_mul_f32 v[156:157], v[208:209], v[156:157] op_sel_hi:[0,1]
	v_pk_fma_f32 v[154:155], v[142:143], v[154:155], v[206:207]
	v_sub_f32_e32 v163, v170, v194
	v_sub_f32_e32 v162, v165, v194
	v_sub_f32_e32 v165, v172, v194
	v_sub_f32_e32 v164, v171, v194
	v_pk_fma_f32 v[156:157], v[144:145], v[156:157], v[204:205]
	v_pk_fma_f32 v[154:155], v[118:119], v[138:139], v[154:155]
	v_pk_mul_f32 v[164:165], v[208:209], v[164:165] op_sel_hi:[0,1]
	v_pk_mul_f32 v[162:163], v[208:209], v[162:163] op_sel_hi:[0,1]
	v_pk_fma_f32 v[156:157], v[120:121], v[140:141], v[156:157]
	v_pk_fma_f32 v[162:163], v[134:135], v[162:163], v[202:203]
	v_pk_fma_f32 v[164:165], v[136:137], v[164:165], v[200:201]
	v_cvt_pk_bf16_f32 v154, v154, v155
	v_cvt_pk_bf16_f32 v155, v156, v157
	v_pk_fma_f32 v[162:163], v[114:115], v[130:131], v[162:163]
	v_pk_fma_f32 v[164:165], v[116:117], v[132:133], v[164:165]
	v_cvt_pk_bf16_f32 v156, v162, v163
	v_lshlrev_b32_e32 v162, 16, v152
	v_cvt_pk_bf16_f32 v157, v164, v165
	global_store_dwordx4 v234, v[154:157], s[46:47]
	v_and_b32_e32 v163, 0xffff0000, v152
	v_lshlrev_b32_e32 v164, 16, v153
	v_lshlrev_b32_e32 v155, 16, v150
	v_and_b32_e32 v150, 0xffff0000, v150
	v_mul_f32_e32 v154, 0x3fd744fd, v193
	v_lshlrev_b32_e32 v156, 16, v151
	v_and_b32_e32 v157, 0xffff0000, v151
	v_sub_f32_e32 v151, v150, v192
	v_sub_f32_e32 v150, v155, v192
	v_and_b32_e32 v165, 0xffff0000, v153
	v_sub_f32_e32 v153, v157, v192
	v_sub_f32_e32 v152, v156, v192
	v_pk_mul_f32 v[150:151], v[154:155], v[150:151] op_sel_hi:[0,1]
	v_pk_mul_f32 v[152:153], v[154:155], v[152:153] op_sel_hi:[0,1]
	v_pk_fma_f32 v[150:151], v[142:143], v[150:151], v[206:207]
	v_sub_f32_e32 v157, v163, v192
	v_sub_f32_e32 v156, v162, v192
	v_sub_f32_e32 v163, v165, v192
	v_sub_f32_e32 v162, v164, v192
	v_pk_fma_f32 v[152:153], v[144:145], v[152:153], v[204:205]
	v_pk_fma_f32 v[150:151], v[110:111], v[138:139], v[150:151]
	v_pk_mul_f32 v[162:163], v[154:155], v[162:163] op_sel_hi:[0,1]
	v_pk_mul_f32 v[156:157], v[154:155], v[156:157] op_sel_hi:[0,1]
	v_pk_fma_f32 v[152:153], v[112:113], v[140:141], v[152:153]
	v_pk_fma_f32 v[156:157], v[134:135], v[156:157], v[202:203]
	v_pk_fma_f32 v[162:163], v[136:137], v[162:163], v[200:201]
	v_cvt_pk_bf16_f32 v150, v150, v151
	v_pk_fma_f32 v[156:157], v[106:107], v[130:131], v[156:157]
	v_pk_fma_f32 v[162:163], v[108:109], v[132:133], v[162:163]
	v_cvt_pk_bf16_f32 v151, v152, v153
	v_cvt_pk_bf16_f32 v152, v156, v157
	v_mul_f32_e32 v156, 0x3fd744fd, v191
	v_cvt_pk_bf16_f32 v153, v162, v163
	global_store_dwordx4 v233, v[150:153], s[46:47]
	v_lshlrev_b32_e32 v157, 16, v149
	v_and_b32_e32 v155, 0xffff0000, v148
	v_lshlrev_b32_e32 v150, 16, v146
	v_and_b32_e32 v146, 0xffff0000, v146
	v_lshlrev_b32_e32 v151, 16, v147
	v_and_b32_e32 v152, 0xffff0000, v147
	v_sub_f32_e32 v147, v146, v190
	v_sub_f32_e32 v146, v150, v190
	v_lshlrev_b32_e32 v153, 16, v148
	v_and_b32_e32 v162, 0xffff0000, v149
	v_sub_f32_e32 v149, v152, v190
	v_sub_f32_e32 v148, v151, v190
	v_pk_mul_f32 v[146:147], v[156:157], v[146:147] op_sel_hi:[0,1]
	v_pk_mul_f32 v[148:149], v[156:157], v[148:149] op_sel_hi:[0,1]
	v_pk_fma_f32 v[146:147], v[142:143], v[146:147], v[206:207]
	v_sub_f32_e32 v151, v155, v190
	v_sub_f32_e32 v150, v153, v190
	v_sub_f32_e32 v153, v162, v190
	v_sub_f32_e32 v152, v157, v190
	v_pk_fma_f32 v[148:149], v[144:145], v[148:149], v[204:205]
	v_pk_fma_f32 v[146:147], v[102:103], v[138:139], v[146:147]
	v_pk_mul_f32 v[152:153], v[156:157], v[152:153] op_sel_hi:[0,1]
	v_pk_mul_f32 v[150:151], v[156:157], v[150:151] op_sel_hi:[0,1]
	v_pk_fma_f32 v[148:149], v[104:105], v[140:141], v[148:149]
	v_pk_fma_f32 v[150:151], v[134:135], v[150:151], v[202:203]
	v_pk_fma_f32 v[152:153], v[136:137], v[152:153], v[200:201]
	v_cvt_pk_bf16_f32 v146, v146, v147
	v_cvt_pk_bf16_f32 v147, v148, v149
	v_pk_fma_f32 v[150:151], v[98:99], v[130:131], v[150:151]
	v_pk_fma_f32 v[152:153], v[100:101], v[132:133], v[152:153]
	v_cvt_pk_bf16_f32 v148, v150, v151
	v_add_u32_e32 v155, 0x90000, v231
	v_cvt_pk_bf16_f32 v149, v152, v153
	global_store_dwordx4 v232, v[146:149], s[46:47]
	v_add_u32_e32 v157, 0xa0000, v231
	v_add_u32_e32 v191, 0xb0000, v231
	v_add_u32_e32 v147, 0x80000, v231
	s_nop 0
	s_nop 0
	s_nop 0
	s_nop 0
	s_waitcnt vmcnt(7)
	v_mul_f32_e32 v146, 0x3fd744fd, v189
	v_lshlrev_b32_e32 v152, 16, v174
	v_and_b32_e32 v148, 0xffff0000, v174
	v_lshlrev_b32_e32 v153, 16, v175
	v_and_b32_e32 v189, 0xffff0000, v175
	v_sub_f32_e32 v149, v148, v188
	v_sub_f32_e32 v148, v152, v188
	v_lshlrev_b32_e32 v193, 16, v176
	v_and_b32_e32 v195, 0xffff0000, v176
	v_lshlrev_b32_e32 v197, 16, v177
	v_and_b32_e32 v231, 0xffff0000, v177
	v_sub_f32_e32 v151, v189, v188
	v_sub_f32_e32 v150, v153, v188
	v_pk_mul_f32 v[148:149], v[146:147], v[148:149] op_sel_hi:[0,1]
	v_pk_mul_f32 v[150:151], v[146:147], v[150:151] op_sel_hi:[0,1]
	v_pk_fma_f32 v[148:149], v[142:143], v[148:149], v[206:207]
	v_sub_f32_e32 v153, v195, v188
	v_sub_f32_e32 v152, v193, v188
	v_sub_f32_e32 v237, v231, v188
	v_sub_f32_e32 v236, v197, v188
	v_pk_fma_f32 v[150:151], v[144:145], v[150:151], v[204:205]
	v_pk_fma_f32 v[148:149], v[94:95], v[138:139], v[148:149]
	v_pk_mul_f32 v[236:237], v[146:147], v[236:237] op_sel_hi:[0,1]
	v_pk_mul_f32 v[152:153], v[146:147], v[152:153] op_sel_hi:[0,1]
	s_waitcnt vmcnt(6)
	s_waitcnt vmcnt(5)
	s_waitcnt vmcnt(4)
	v_pk_fma_f32 v[150:151], v[96:97], v[140:141], v[150:151]
	v_pk_fma_f32 v[152:153], v[134:135], v[152:153], v[202:203]
	v_pk_fma_f32 v[236:237], v[136:137], v[236:237], v[200:201]
	v_cvt_pk_bf16_f32 v148, v148, v149
	v_cvt_pk_bf16_f32 v149, v150, v151
	v_pk_fma_f32 v[152:153], v[90:91], v[130:131], v[152:153]
	v_pk_fma_f32 v[236:237], v[92:93], v[132:133], v[236:237]
	v_cvt_pk_bf16_f32 v150, v152, v153
	v_lshlrev_b32_e32 v152, 16, v179
	v_cvt_pk_bf16_f32 v151, v236, v237
	global_store_dwordx4 v147, v[148:151], s[46:47]
	v_lshlrev_b32_e32 v147, 16, v178
	v_and_b32_e32 v153, 0xffff0000, v179
	v_and_b32_e32 v149, 0xffff0000, v178
	v_mul_f32_e32 v148, 0x3fd744fd, v187
	v_sub_f32_e32 v151, v149, v186
	v_sub_f32_e32 v150, v147, v186
	v_lshlrev_b32_e32 v162, 16, v180
	v_and_b32_e32 v163, 0xffff0000, v180
	v_lshlrev_b32_e32 v164, 16, v181
	v_and_b32_e32 v165, 0xffff0000, v181
	v_sub_f32_e32 v153, v153, v186
	v_sub_f32_e32 v152, v152, v186
	v_pk_mul_f32 v[150:151], v[148:149], v[150:151] op_sel_hi:[0,1]
	v_pk_mul_f32 v[152:153], v[148:149], v[152:153] op_sel_hi:[0,1]
	v_pk_fma_f32 v[150:151], v[142:143], v[150:151], v[206:207]
	v_sub_f32_e32 v163, v163, v186
	v_sub_f32_e32 v162, v162, v186
	v_sub_f32_e32 v165, v165, v186
	v_sub_f32_e32 v164, v164, v186
	v_pk_fma_f32 v[152:153], v[144:145], v[152:153], v[204:205]
	v_pk_fma_f32 v[150:151], v[86:87], v[138:139], v[150:151]
	v_pk_mul_f32 v[164:165], v[148:149], v[164:165] op_sel_hi:[0,1]
	v_pk_mul_f32 v[162:163], v[148:149], v[162:163] op_sel_hi:[0,1]
	v_pk_fma_f32 v[152:153], v[88:89], v[140:141], v[152:153]
	v_pk_fma_f32 v[162:163], v[134:135], v[162:163], v[202:203]
	v_pk_fma_f32 v[164:165], v[136:137], v[164:165], v[200:201]
	v_cvt_pk_bf16_f32 v150, v150, v151
	v_cvt_pk_bf16_f32 v151, v152, v153
	v_pk_fma_f32 v[162:163], v[82:83], v[130:131], v[162:163]
	v_pk_fma_f32 v[164:165], v[84:85], v[132:133], v[164:165]
	v_cvt_pk_bf16_f32 v152, v162, v163
	v_lshlrev_b32_e32 v147, 16, v240
	v_cvt_pk_bf16_f32 v153, v164, v165
	global_store_dwordx4 v155, v[150:153], s[46:47]
	v_and_b32_e32 v155, 0xffff0000, v241
	v_sub_f32_e32 v163, v155, v184
	v_lshlrev_b32_e32 v151, 16, v241
	v_mul_f32_e32 v150, 0x3fd744fd, v185
	v_sub_f32_e32 v162, v151, v184
	v_and_b32_e32 v149, 0xffff0000, v240
	v_pk_mul_f32 v[162:163], v[150:151], v[162:163] op_sel_hi:[0,1]
	v_lshlrev_b32_e32 v170, 16, v242
	v_and_b32_e32 v171, 0xffff0000, v242
	v_lshlrev_b32_e32 v172, 16, v243
	v_and_b32_e32 v173, 0xffff0000, v243
	v_sub_f32_e32 v153, v149, v184
	v_sub_f32_e32 v152, v147, v184
	v_pk_fma_f32 v[162:163], v[144:145], v[162:163], v[204:205]
	v_pk_mul_f32 v[152:153], v[150:151], v[152:153] op_sel_hi:[0,1]
	v_pk_fma_f32 v[164:165], v[80:81], v[140:141], v[162:163]
	v_sub_f32_e32 v163, v171, v184
	v_sub_f32_e32 v162, v170, v184
	v_sub_f32_e32 v171, v173, v184
	v_sub_f32_e32 v170, v172, v184
	v_pk_fma_f32 v[152:153], v[142:143], v[152:153], v[206:207]
	v_pk_mul_f32 v[170:171], v[150:151], v[170:171] op_sel_hi:[0,1]
	v_pk_mul_f32 v[162:163], v[150:151], v[162:163] op_sel_hi:[0,1]
	v_pk_fma_f32 v[152:153], v[78:79], v[138:139], v[152:153]
	v_pk_fma_f32 v[162:163], v[134:135], v[162:163], v[202:203]
	v_pk_fma_f32 v[170:171], v[136:137], v[170:171], v[200:201]
	v_pk_fma_f32 v[172:173], v[74:75], v[130:131], v[162:163]
	v_pk_fma_f32 v[170:171], v[76:77], v[132:133], v[170:171]
	v_cvt_pk_bf16_f32 v162, v152, v153
	v_cvt_pk_bf16_f32 v163, v164, v165
	v_cvt_pk_bf16_f32 v164, v172, v173
	v_lshlrev_b32_e32 v147, 16, v244
	v_cvt_pk_bf16_f32 v165, v170, v171
	v_and_b32_e32 v149, 0xffff0000, v244
	v_lshlrev_b32_e32 v151, 16, v245
	v_and_b32_e32 v153, 0xffff0000, v245
	global_store_dwordx4 v157, v[162:165], s[46:47]
	v_mul_f32_e32 v152, 0x3fd744fd, v183
	v_lshlrev_b32_e32 v155, 16, v246
	v_sub_f32_e32 v163, v149, v182
	v_sub_f32_e32 v162, v147, v182
	v_sub_f32_e32 v165, v153, v182
	v_sub_f32_e32 v164, v151, v182
	v_pk_mul_f32 v[164:165], v[152:153], v[164:165] op_sel_hi:[0,1]
	v_pk_mul_f32 v[162:163], v[152:153], v[162:163] op_sel_hi:[0,1]
	v_and_b32_e32 v157, 0xffff0000, v246
	v_lshlrev_b32_e32 v170, 16, v247
	v_and_b32_e32 v171, 0xffff0000, v247
	v_pk_fma_f32 v[142:143], v[142:143], v[162:163], v[206:207]
	v_pk_fma_f32 v[144:145], v[144:145], v[164:165], v[204:205]
	v_pk_fma_f32 v[138:139], v[70:71], v[138:139], v[142:143]
	v_pk_fma_f32 v[140:141], v[72:73], v[140:141], v[144:145]
	v_sub_f32_e32 v143, v157, v182
	v_sub_f32_e32 v142, v155, v182
	v_sub_f32_e32 v145, v171, v182
	v_sub_f32_e32 v144, v170, v182
	v_pk_mul_f32 v[144:145], v[152:153], v[144:145] op_sel_hi:[0,1]
	v_pk_mul_f32 v[142:143], v[152:153], v[142:143] op_sel_hi:[0,1]
	v_pk_fma_f32 v[134:135], v[134:135], v[142:143], v[202:203]
	v_pk_fma_f32 v[136:137], v[136:137], v[144:145], v[200:201]
	v_add_u32_e32 v147, 0x80, v230
	v_pk_fma_f32 v[136:137], v[68:69], v[132:133], v[136:137]
	v_pk_fma_f32 v[132:133], v[66:67], v[130:131], v[134:135]
	v_cvt_pk_bf16_f32 v130, v138, v139
	v_cvt_pk_bf16_f32 v131, v140, v141
	v_lshlrev_b32_e32 v149, 2, v147
	v_cvt_pk_bf16_f32 v132, v132, v133
	v_cvt_pk_bf16_f32 v133, v136, v137
	global_store_dwordx4 v191, v[130:133], s[46:47]
	global_load_dwordx4 v[130:133], v149, s[54:55] offset:16
	s_nop 0
	global_load_dwordx4 v[138:141], v149, s[54:55]
	global_load_dwordx4 v[134:137], v149, s[38:39] offset:16
	global_load_dwordx4 v[142:145], v149, s[38:39]
	global_load_dwordx4 v[162:165], v149, s[0:1] offset:16
	global_load_dwordx4 v[170:173], v149, s[0:1]
	v_lshl_add_u32 v147, v147, 1, v227
	v_add_u32_e32 v149, 0x10000, v147
	v_add_u32_e32 v151, 0x20000, v147
	v_add_u32_e32 v153, 0x30000, v147
	global_load_dwordx4 v[230:233], v151, s[42:43]
	global_load_dwordx4 v[234:237], v153, s[42:43]
	s_waitcnt vmcnt(3)
	v_pk_mul_f32 v[200:201], v[164:165], s[76:77] op_sel_hi:[1,0]
	v_pk_mul_f32 v[202:203], v[162:163], s[76:77] op_sel_hi:[1,0]
	global_load_dwordx4 v[162:165], v147, s[42:43]
	s_waitcnt vmcnt(3)
	v_pk_mul_f32 v[204:205], v[172:173], s[76:77] op_sel_hi:[1,0]
	v_pk_mul_f32 v[206:207], v[170:171], s[76:77] op_sel_hi:[1,0]
	global_load_dwordx4 v[170:173], v149, s[42:43]
	v_add_u32_e32 v158, 0x80000, v147
	global_load_dwordx4 v[174:177], v158, s[42:43]
	v_add_u32_e32 v158, 0x90000, v147
	global_load_dwordx4 v[178:181], v158, s[42:43]
	v_add_u32_e32 v158, 0xa0000, v147
	global_load_dwordx4 v[240:243], v158, s[42:43]
	v_add_u32_e32 v158, 0xb0000, v147
	global_load_dwordx4 v[244:247], v158, s[42:43]
	s_waitcnt vmcnt(5)
	s_waitcnt vmcnt(4)
	v_lshlrev_b32_e32 v155, 16, v162
	v_and_b32_e32 v157, 0xffff0000, v162
	v_lshlrev_b32_e32 v183, 16, v163
	v_and_b32_e32 v185, 0xffff0000, v163
	v_lshlrev_b32_e32 v187, 16, v164
	v_and_b32_e32 v189, 0xffff0000, v164
	v_lshlrev_b32_e32 v191, 16, v165
	v_and_b32_e32 v193, 0xffff0000, v165
	v_sub_f32_e32 v163, v157, v196
	v_sub_f32_e32 v162, v155, v196
	v_sub_f32_e32 v165, v185, v196
	v_sub_f32_e32 v164, v183, v196
	v_pk_mul_f32 v[164:165], v[198:199], v[164:165] op_sel_hi:[0,1]
	v_pk_mul_f32 v[162:163], v[198:199], v[162:163] op_sel_hi:[0,1]
	v_sub_f32_e32 v239, v189, v196
	v_sub_f32_e32 v238, v187, v196
	v_sub_f32_e32 v197, v193, v196
	v_sub_f32_e32 v196, v191, v196
	v_pk_fma_f32 v[162:163], v[142:143], v[162:163], v[206:207]
	v_pk_fma_f32 v[164:165], v[144:145], v[164:165], v[204:205]
	v_pk_mul_f32 v[196:197], v[198:199], v[196:197] op_sel_hi:[0,1]
	v_pk_mul_f32 v[238:239], v[198:199], v[238:239] op_sel_hi:[0,1]
	v_pk_fma_f32 v[164:165], v[62:63], v[140:141], v[164:165]
	v_pk_fma_f32 v[162:163], v[60:61], v[138:139], v[162:163]
	v_pk_fma_f32 v[238:239], v[134:135], v[238:239], v[202:203]
	v_pk_fma_f32 v[196:197], v[136:137], v[196:197], v[200:201]
	v_pk_fma_f32 v[238:239], v[56:57], v[130:131], v[238:239]
	v_pk_fma_f32 v[196:197], v[58:59], v[132:133], v[196:197]
	v_cvt_pk_bf16_f32 v162, v162, v163
	v_cvt_pk_bf16_f32 v163, v164, v165
	v_cvt_pk_bf16_f32 v164, v238, v239
	v_lshlrev_b32_e32 v155, 16, v170
	v_cvt_pk_bf16_f32 v165, v196, v197
	global_store_dwordx4 v147, v[162:165], s[46:47]
	v_and_b32_e32 v157, 0xffff0000, v170
	v_lshlrev_b32_e32 v170, 16, v172
	v_lshlrev_b32_e32 v164, 16, v171
	v_and_b32_e32 v165, 0xffff0000, v171
	v_and_b32_e32 v171, 0xffff0000, v172
	v_sub_f32_e32 v163, v157, v194
	v_sub_f32_e32 v162, v155, v194
	v_sub_f32_e32 v165, v165, v194
	v_sub_f32_e32 v164, v164, v194
	v_lshlrev_b32_e32 v172, 16, v173
	v_and_b32_e32 v173, 0xffff0000, v173
	v_pk_mul_f32 v[164:165], v[208:209], v[164:165] op_sel_hi:[0,1]
	v_pk_mul_f32 v[162:163], v[208:209], v[162:163] op_sel_hi:[0,1]
	v_sub_f32_e32 v171, v171, v194
	v_sub_f32_e32 v170, v170, v194
	v_pk_fma_f32 v[162:163], v[142:143], v[162:163], v[206:207]
	v_pk_fma_f32 v[164:165], v[144:145], v[164:165], v[204:205]
	v_sub_f32_e32 v173, v173, v194
	v_sub_f32_e32 v172, v172, v194
	v_pk_mul_f32 v[170:171], v[208:209], v[170:171] op_sel_hi:[0,1]
	v_pk_fma_f32 v[164:165], v[54:55], v[140:141], v[164:165]
	v_pk_fma_f32 v[162:163], v[52:53], v[138:139], v[162:163]
	v_pk_mul_f32 v[172:173], v[208:209], v[172:173] op_sel_hi:[0,1]
	v_pk_fma_f32 v[170:171], v[134:135], v[170:171], v[202:203]
	v_pk_fma_f32 v[172:173], v[136:137], v[172:173], v[200:201]
	v_pk_fma_f32 v[170:171], v[48:49], v[130:131], v[170:171]
	v_cvt_pk_bf16_f32 v162, v162, v163
	v_cvt_pk_bf16_f32 v163, v164, v165
	v_pk_fma_f32 v[172:173], v[50:51], v[132:133], v[172:173]
	v_cvt_pk_bf16_f32 v164, v170, v171
	v_and_b32_e32 v155, 0xffff0000, v230
	v_cvt_pk_bf16_f32 v165, v172, v173
	global_store_dwordx4 v149, v[162:165], s[46:47]
	v_lshlrev_b32_e32 v149, 16, v230
	v_lshlrev_b32_e32 v157, 16, v231
	v_and_b32_e32 v164, 0xffff0000, v231
	v_lshlrev_b32_e32 v170, 16, v232
	v_and_b32_e32 v171, 0xffff0000, v232
	v_lshlrev_b32_e32 v172, 16, v233
	v_and_b32_e32 v173, 0xffff0000, v233
	v_sub_f32_e32 v163, v155, v192
	v_sub_f32_e32 v162, v149, v192
	v_sub_f32_e32 v165, v164, v192
	v_sub_f32_e32 v164, v157, v192
	v_pk_mul_f32 v[164:165], v[154:155], v[164:165] op_sel_hi:[0,1]
	v_pk_mul_f32 v[162:163], v[154:155], v[162:163] op_sel_hi:[0,1]
	v_sub_f32_e32 v171, v171, v192
	v_sub_f32_e32 v170, v170, v192
	v_sub_f32_e32 v173, v173, v192
	v_sub_f32_e32 v172, v172, v192
	v_pk_fma_f32 v[162:163], v[142:143], v[162:163], v[206:207]
	v_pk_fma_f32 v[164:165], v[144:145], v[164:165], v[204:205]
	v_pk_mul_f32 v[172:173], v[154:155], v[172:173] op_sel_hi:[0,1]
	v_pk_mul_f32 v[154:155], v[154:155], v[170:171] op_sel_hi:[0,1]
	v_pk_fma_f32 v[164:165], v[46:47], v[140:141], v[164:165]
	v_pk_fma_f32 v[162:163], v[44:45], v[138:139], v[162:163]
	v_pk_fma_f32 v[154:155], v[134:135], v[154:155], v[202:203]
	v_pk_fma_f32 v[170:171], v[136:137], v[172:173], v[200:201]
	v_pk_fma_f32 v[154:155], v[40:41], v[130:131], v[154:155]
	v_pk_fma_f32 v[170:171], v[42:43], v[132:133], v[170:171]
	v_cvt_pk_bf16_f32 v162, v162, v163
	v_cvt_pk_bf16_f32 v163, v164, v165
	v_cvt_pk_bf16_f32 v164, v154, v155
	v_lshlrev_b32_e32 v149, 16, v234
	v_cvt_pk_bf16_f32 v165, v170, v171
	global_store_dwordx4 v151, v[162:165], s[46:47]
	v_and_b32_e32 v151, 0xffff0000, v234
	v_lshlrev_b32_e32 v157, 16, v235
	v_and_b32_e32 v162, 0xffff0000, v235
	v_lshlrev_b32_e32 v164, 16, v236
	v_and_b32_e32 v165, 0xffff0000, v236
	v_lshlrev_b32_e32 v170, 16, v237
	v_and_b32_e32 v171, 0xffff0000, v237
	v_sub_f32_e32 v155, v151, v190
	v_sub_f32_e32 v154, v149, v190
	v_sub_f32_e32 v163, v162, v190
	v_sub_f32_e32 v162, v157, v190
	v_sub_f32_e32 v165, v165, v190
	v_sub_f32_e32 v164, v164, v190
	v_sub_f32_e32 v171, v171, v190
	v_sub_f32_e32 v170, v170, v190
	v_pk_mul_f32 v[162:163], v[156:157], v[162:163] op_sel_hi:[0,1]
	v_pk_mul_f32 v[154:155], v[156:157], v[154:155] op_sel_hi:[0,1]
	v_pk_mul_f32 v[170:171], v[156:157], v[170:171] op_sel_hi:[0,1]
	v_pk_mul_f32 v[156:157], v[156:157], v[164:165] op_sel_hi:[0,1]
	v_pk_fma_f32 v[154:155], v[142:143], v[154:155], v[206:207]
	v_pk_fma_f32 v[156:157], v[134:135], v[156:157], v[202:203]
	v_pk_fma_f32 v[162:163], v[144:145], v[162:163], v[204:205]
	v_pk_fma_f32 v[154:155], v[36:37], v[138:139], v[154:155]
	v_pk_fma_f32 v[164:165], v[136:137], v[170:171], v[200:201]
	v_pk_fma_f32 v[156:157], v[32:33], v[130:131], v[156:157]
	v_pk_fma_f32 v[162:163], v[38:39], v[140:141], v[162:163]
	v_pk_fma_f32 v[164:165], v[34:35], v[132:133], v[164:165]
	v_cvt_pk_bf16_f32 v154, v154, v155
	v_cvt_pk_bf16_f32 v155, v162, v163
	v_cvt_pk_bf16_f32 v156, v156, v157
	v_add_u32_e32 v149, 0x80000, v147
	v_cvt_pk_bf16_f32 v157, v164, v165
	global_store_dwordx4 v153, v[154:157], s[46:47]
	s_nop 0
	v_add_u32_e32 v151, 0x90000, v147
	v_add_u32_e32 v153, 0xa0000, v147
	v_add_u32_e32 v154, 0xb0000, v147
	s_nop 0
	s_nop 0
	s_nop 0
	s_waitcnt vmcnt(7)
	s_waitcnt vmcnt(6)
	s_waitcnt vmcnt(5)
	s_waitcnt vmcnt(4)
	v_mov_b32_e32 v155, v64
	v_lshlrev_b32_e32 v147, 16, v174
	v_and_b32_e32 v156, 0xffff0000, v174
	v_lshlrev_b32_e32 v162, 16, v175
	v_and_b32_e32 v163, 0xffff0000, v175
	v_sub_f32_e32 v163, v163, v188
	v_sub_f32_e32 v162, v162, v188
	v_pk_mul_f32 v[162:163], v[146:147], v[162:163] op_sel_hi:[0,1]
	v_lshlrev_b32_e32 v183, 16, v176
	v_and_b32_e32 v185, 0xffff0000, v176
	v_lshlrev_b32_e32 v187, 16, v177
	v_and_b32_e32 v189, 0xffff0000, v177
	v_pk_fma_f32 v[162:163], v[144:145], v[162:163], v[204:205]
	v_sub_f32_e32 v157, v156, v188
	v_sub_f32_e32 v156, v147, v188
	v_pk_fma_f32 v[164:165], v[30:31], v[140:141], v[162:163]
	v_sub_f32_e32 v163, v185, v188
	v_sub_f32_e32 v162, v183, v188
	v_sub_f32_e32 v189, v189, v188
	v_sub_f32_e32 v188, v187, v188
	v_pk_mul_f32 v[156:157], v[146:147], v[156:157] op_sel_hi:[0,1]
	v_pk_mul_f32 v[188:189], v[146:147], v[188:189] op_sel_hi:[0,1]
	v_pk_mul_f32 v[146:147], v[146:147], v[162:163] op_sel_hi:[0,1]
	v_pk_fma_f32 v[156:157], v[142:143], v[156:157], v[206:207]
	v_pk_fma_f32 v[146:147], v[134:135], v[146:147], v[202:203]
	v_pk_fma_f32 v[162:163], v[136:137], v[188:189], v[200:201]
	v_pk_fma_f32 v[156:157], v[28:29], v[138:139], v[156:157]
	v_pk_fma_f32 v[188:189], v[26:27], v[132:133], v[162:163]
	v_pk_fma_f32 v[146:147], v[24:25], v[130:131], v[146:147]
	v_cvt_pk_bf16_f32 v162, v156, v157
	v_cvt_pk_bf16_f32 v163, v164, v165
	v_and_b32_e32 v156, 0xffff0000, v179
	v_cvt_pk_bf16_f32 v164, v146, v147
	v_cvt_pk_bf16_f32 v165, v188, v189
	global_store_dwordx4 v149, v[162:165], s[46:47]
	v_lshlrev_b32_e32 v146, 16, v178
	v_and_b32_e32 v147, 0xffff0000, v178
	v_lshlrev_b32_e32 v149, 16, v179
	v_lshlrev_b32_e32 v162, 16, v180
	v_and_b32_e32 v163, 0xffff0000, v180
	v_lshlrev_b32_e32 v164, 16, v181
	v_and_b32_e32 v165, 0xffff0000, v181
	v_sub_f32_e32 v147, v147, v186
	v_sub_f32_e32 v146, v146, v186
	v_sub_f32_e32 v157, v156, v186
	v_sub_f32_e32 v156, v149, v186
	v_sub_f32_e32 v163, v163, v186
	v_sub_f32_e32 v162, v162, v186
	v_sub_f32_e32 v165, v165, v186
	v_sub_f32_e32 v164, v164, v186
	v_pk_mul_f32 v[156:157], v[148:149], v[156:157] op_sel_hi:[0,1]
	v_pk_mul_f32 v[146:147], v[148:149], v[146:147] op_sel_hi:[0,1]
	v_pk_mul_f32 v[164:165], v[148:149], v[164:165] op_sel_hi:[0,1]
	v_pk_mul_f32 v[148:149], v[148:149], v[162:163] op_sel_hi:[0,1]
	v_pk_fma_f32 v[146:147], v[142:143], v[146:147], v[206:207]
	v_pk_fma_f32 v[148:149], v[134:135], v[148:149], v[202:203]
	v_pk_fma_f32 v[156:157], v[144:145], v[156:157], v[204:205]
	v_pk_fma_f32 v[146:147], v[20:21], v[138:139], v[146:147]
	v_pk_fma_f32 v[162:163], v[136:137], v[164:165], v[200:201]
	v_pk_fma_f32 v[148:149], v[16:17], v[130:131], v[148:149]
	v_pk_fma_f32 v[156:157], v[22:23], v[140:141], v[156:157]
	v_pk_fma_f32 v[162:163], v[18:19], v[132:133], v[162:163]
	v_cvt_pk_bf16_f32 v146, v146, v147
	v_cvt_pk_bf16_f32 v147, v156, v157
	v_cvt_pk_bf16_f32 v148, v148, v149
	v_and_b32_e32 v156, 0xffff0000, v242
	v_cvt_pk_bf16_f32 v149, v162, v163
	global_store_dwordx4 v151, v[146:149], s[46:47]
	v_lshlrev_b32_e32 v151, 16, v242
	v_lshlrev_b32_e32 v162, 16, v243
	v_lshlrev_b32_e32 v146, 16, v240
	v_and_b32_e32 v147, 0xffff0000, v240
	v_lshlrev_b32_e32 v148, 16, v241
	v_and_b32_e32 v149, 0xffff0000, v241
	v_and_b32_e32 v163, 0xffff0000, v243
	v_sub_f32_e32 v147, v147, v184
	v_sub_f32_e32 v146, v146, v184
	v_sub_f32_e32 v149, v149, v184
	v_sub_f32_e32 v148, v148, v184
	v_pk_mul_f32 v[148:149], v[150:151], v[148:149] op_sel_hi:[0,1]
	v_pk_mul_f32 v[146:147], v[150:151], v[146:147] op_sel_hi:[0,1]
	v_sub_f32_e32 v157, v156, v184
	v_sub_f32_e32 v156, v151, v184
	v_sub_f32_e32 v163, v163, v184
	v_sub_f32_e32 v162, v162, v184
	v_pk_fma_f32 v[146:147], v[142:143], v[146:147], v[206:207]
	v_pk_fma_f32 v[148:149], v[144:145], v[148:149], v[204:205]
	v_pk_mul_f32 v[162:163], v[150:151], v[162:163] op_sel_hi:[0,1]
	v_pk_mul_f32 v[150:151], v[150:151], v[156:157] op_sel_hi:[0,1]
	v_pk_fma_f32 v[148:149], v[14:15], v[140:141], v[148:149]
	v_pk_fma_f32 v[146:147], v[12:13], v[138:139], v[146:147]
	v_pk_fma_f32 v[150:151], v[134:135], v[150:151], v[202:203]
	v_pk_fma_f32 v[156:157], v[136:137], v[162:163], v[200:201]
	v_pk_fma_f32 v[150:151], v[8:9], v[130:131], v[150:151]
	v_pk_fma_f32 v[156:157], v[10:11], v[132:133], v[156:157]
	v_cvt_pk_bf16_f32 v146, v146, v147
	v_cvt_pk_bf16_f32 v147, v148, v149
	v_cvt_pk_bf16_f32 v148, v150, v151
	v_lshlrev_b32_e32 v150, 16, v246
	v_cvt_pk_bf16_f32 v149, v156, v157
	global_store_dwordx4 v153, v[146:149], s[46:47]
	v_lshlrev_b32_e32 v153, 16, v247
	v_and_b32_e32 v151, 0xffff0000, v246
	v_lshlrev_b32_e32 v146, 16, v244
	v_and_b32_e32 v147, 0xffff0000, v244
	v_lshlrev_b32_e32 v148, 16, v245
	v_and_b32_e32 v149, 0xffff0000, v245
	v_sub_f32_e32 v147, v147, v182
	v_sub_f32_e32 v146, v146, v182
	v_sub_f32_e32 v149, v149, v182
	v_sub_f32_e32 v148, v148, v182
	v_pk_mul_f32 v[148:149], v[152:153], v[148:149] op_sel_hi:[0,1]
	v_pk_mul_f32 v[146:147], v[152:153], v[146:147] op_sel_hi:[0,1]
	v_and_b32_e32 v156, 0xffff0000, v247
	v_pk_fma_f32 v[142:143], v[142:143], v[146:147], v[206:207]
	v_pk_fma_f32 v[144:145], v[144:145], v[148:149], v[204:205]
	v_pk_fma_f32 v[138:139], v[4:5], v[138:139], v[142:143]
	v_pk_fma_f32 v[140:141], v[6:7], v[140:141], v[144:145]
	v_sub_f32_e32 v143, v151, v182
	v_sub_f32_e32 v142, v150, v182
	v_sub_f32_e32 v145, v156, v182
	v_sub_f32_e32 v144, v153, v182
	v_pk_mul_f32 v[144:145], v[152:153], v[144:145] op_sel_hi:[0,1]
	v_pk_mul_f32 v[142:143], v[152:153], v[142:143] op_sel_hi:[0,1]
	v_pk_fma_f32 v[134:135], v[134:135], v[142:143], v[202:203]
	v_pk_fma_f32 v[136:137], v[136:137], v[144:145], v[200:201]
	s_nop 0
	v_pk_fma_f32 v[136:137], v[2:3], v[132:133], v[136:137]
	v_pk_fma_f32 v[132:133], v[0:1], v[130:131], v[134:135]
	v_cvt_pk_bf16_f32 v130, v138, v139
	v_cvt_pk_bf16_f32 v131, v140, v141
	s_nop 0
	v_cvt_pk_bf16_f32 v132, v132, v133
	v_cvt_pk_bf16_f32 v133, v136, v137
	s_cbranch_execnz .LBB0_906

.LBB0_1330:
	v_mov_b32_e32 v130, v65
	v_mov_b32_e32 v131, v199
	s_lshl_b32 s21, s83, 8
	s_ashr_i32 s20, s83, 4
	s_add_i32 s21, s21, s63
	v_add_u32_e32 v131, s21, v131
	s_mul_i32 s20, s20, 6
	s_ashr_i32 s21, s20, 31
	v_lshlrev_b32_e32 v132, 3, v131
	s_lshl_b64 s[20:21], s[20:21], 13
	v_add_u32_e32 v133, 0x80, v132
	s_add_u32 s20, s61, s20
	global_load_dwordx2 v[196:197], v132, s[6:7]
	global_load_dwordx2 v[194:195], v133, s[6:7]
	v_add_u32_e32 v133, 0x100, v132
	s_addc_u32 s21, s62, s21
	global_load_dwordx2 v[192:193], v133, s[6:7]
	v_add_u32_e32 v133, 0x180, v132
	s_lshl_b32 s22, s82, 8
	global_load_dwordx2 v[190:191], v133, s[6:7]
	v_add_u32_e32 v133, 0x400, v132
	s_or_b32 s22, s22, s64
	global_load_dwordx2 v[188:189], v133, s[6:7]
	v_add_u32_e32 v133, 0x480, v132
	v_lshl_add_u32 v227, v130, 3, s22
	global_load_dwordx2 v[186:187], v133, s[6:7]
	v_add_u32_e32 v133, 0x500, v132
	v_add_u32_e32 v132, 0x580, v132
	v_lshlrev_b32_e32 v150, 2, v227
	global_load_dwordx2 v[184:185], v133, s[6:7]
	global_load_dwordx2 v[182:183], v132, s[6:7]
	v_lshlrev_b32_e32 v226, 12, v131
	global_load_dwordx4 v[130:133], v150, s[20:21] offset:16
	global_load_dwordx4 v[138:141], v150, s[20:21]
	global_load_dwordx4 v[134:137], v150, s[4:5] offset:16
	global_load_dwordx4 v[142:145], v150, s[4:5]
	global_load_dwordx4 v[146:149], v150, s[0:1] offset:16
	s_nop 0
	global_load_dwordx4 v[150:153], v150, s[0:1]
	v_lshl_add_u32 v228, v227, 1, v226
	global_load_dwordx4 v[162:165], v228, s[46:47]
	v_add_u32_e32 v231, 0x10000, v228
	v_add_u32_e32 v230, 0x20000, v228
	v_add_u32_e32 v229, 0x30000, v228
	global_load_dwordx4 v[154:157], v231, s[46:47]
	s_and_b64 vcc, exec, s[36:37]
	s_mov_b64 s[84:85], 0x400
	s_waitcnt vmcnt(0)
	v_mul_f32_e32 v198, 0x3fd744fd, v197
	v_pk_mul_f32 v[200:201], v[148:149], s[76:77] op_sel_hi:[1,0]
	v_pk_mul_f32 v[204:205], v[152:153], s[76:77] op_sel_hi:[1,0]
	v_pk_mul_f32 v[206:207], v[150:151], s[76:77] op_sel_hi:[1,0]
	v_pk_mul_f32 v[202:203], v[146:147], s[76:77] op_sel_hi:[1,0]
	global_load_dwordx4 v[150:153], v230, s[46:47]
	global_load_dwordx4 v[146:149], v229, s[46:47]
	v_add_u32_e32 v246, 0x90000, v228
	global_load_dwordx4 v[238:241], v246, s[46:47]
	v_add_u32_e32 v246, 0x80000, v228
	global_load_dwordx4 v[234:237], v246, s[46:47]
	v_add_u32_e32 v246, 0xa0000, v228
	global_load_dwordx4 v[242:245], v246, s[46:47]
	v_add_u32_e32 v246, 0xb0000, v228
	global_load_dwordx4 v[174:177], v246, s[46:47]
	s_waitcnt vmcnt(5)
	s_waitcnt vmcnt(4)
	v_lshlrev_b32_e32 v170, 16, v162
	v_and_b32_e32 v162, 0xffff0000, v162
	v_lshlrev_b32_e32 v171, 16, v163
	v_and_b32_e32 v172, 0xffff0000, v163
	v_lshlrev_b32_e32 v173, 16, v164
	v_and_b32_e32 v197, 0xffff0000, v164
	v_lshlrev_b32_e32 v232, 16, v165
	v_and_b32_e32 v233, 0xffff0000, v165
	v_sub_f32_e32 v163, v162, v196
	v_sub_f32_e32 v162, v170, v196
	v_sub_f32_e32 v165, v172, v196
	v_sub_f32_e32 v164, v171, v196
	v_pk_mul_f32 v[164:165], v[198:199], v[164:165] op_sel_hi:[0,1]
	v_pk_mul_f32 v[162:163], v[198:199], v[162:163] op_sel_hi:[0,1]
	v_pk_fma_f32 v[162:163], v[142:143], v[162:163], v[206:207]
	v_pk_fma_f32 v[164:165], v[144:145], v[164:165], v[204:205]
	v_pk_fma_f32 v[126:127], v[126:127], v[138:139], v[162:163]
	v_pk_fma_f32 v[128:129], v[128:129], v[140:141], v[164:165]
	v_sub_f32_e32 v163, v197, v196
	v_sub_f32_e32 v162, v173, v196
	v_sub_f32_e32 v165, v233, v196
	v_sub_f32_e32 v164, v232, v196
	v_pk_mul_f32 v[164:165], v[198:199], v[164:165] op_sel_hi:[0,1]
	v_pk_mul_f32 v[162:163], v[198:199], v[162:163] op_sel_hi:[0,1]
	v_pk_fma_f32 v[162:163], v[134:135], v[162:163], v[202:203]
	v_pk_fma_f32 v[164:165], v[136:137], v[164:165], v[200:201]
	s_nop 0
	v_pk_fma_f32 v[164:165], v[124:125], v[132:133], v[164:165]
	v_pk_fma_f32 v[124:125], v[122:123], v[130:131], v[162:163]
	v_cvt_pk_bf16_f32 v122, v126, v127
	v_cvt_pk_bf16_f32 v123, v128, v129
	v_lshlrev_b32_e32 v126, 16, v155
	v_cvt_pk_bf16_f32 v124, v124, v125
	v_cvt_pk_bf16_f32 v125, v164, v165
	global_store_dwordx4 v228, v[122:125], s[42:43]
	v_and_b32_e32 v127, 0xffff0000, v155
	v_sub_f32_e32 v127, v127, v194
	v_lshlrev_b32_e32 v123, 16, v154
	v_and_b32_e32 v124, 0xffff0000, v154
	v_mul_f32_e32 v122, 0x3fd744fd, v195
	v_sub_f32_e32 v125, v124, v194
	v_sub_f32_e32 v124, v123, v194
	v_sub_f32_e32 v126, v126, v194
	v_pk_mul_f32 v[126:127], v[122:123], v[126:127] op_sel_hi:[0,1]
	v_pk_mul_f32 v[124:125], v[122:123], v[124:125] op_sel_hi:[0,1]
	v_lshlrev_b32_e32 v128, 16, v156
	v_and_b32_e32 v129, 0xffff0000, v156
	v_lshlrev_b32_e32 v154, 16, v157
	v_and_b32_e32 v155, 0xffff0000, v157
	v_pk_fma_f32 v[124:125], v[142:143], v[124:125], v[206:207]
	v_pk_fma_f32 v[126:127], v[144:145], v[126:127], v[204:205]
	v_pk_fma_f32 v[118:119], v[118:119], v[138:139], v[124:125]
	v_pk_fma_f32 v[120:121], v[120:121], v[140:141], v[126:127]
	v_sub_f32_e32 v125, v129, v194
	v_sub_f32_e32 v124, v128, v194
	v_sub_f32_e32 v127, v155, v194
	v_sub_f32_e32 v126, v154, v194
	v_pk_mul_f32 v[126:127], v[122:123], v[126:127] op_sel_hi:[0,1]
	v_pk_mul_f32 v[124:125], v[122:123], v[124:125] op_sel_hi:[0,1]
	v_pk_fma_f32 v[124:125], v[134:135], v[124:125], v[202:203]
	v_pk_fma_f32 v[126:127], v[136:137], v[126:127], v[200:201]
	v_lshlrev_b32_e32 v123, 16, v153
	v_pk_fma_f32 v[126:127], v[116:117], v[132:133], v[126:127]
	v_pk_fma_f32 v[116:117], v[114:115], v[130:131], v[124:125]
	v_cvt_pk_bf16_f32 v114, v118, v119
	v_cvt_pk_bf16_f32 v115, v120, v121
	v_lshlrev_b32_e32 v118, 16, v151
	v_cvt_pk_bf16_f32 v116, v116, v117
	v_cvt_pk_bf16_f32 v117, v126, v127
	global_store_dwordx4 v231, v[114:117], s[42:43]
	v_and_b32_e32 v119, 0xffff0000, v151
	v_sub_f32_e32 v119, v119, v192
	v_lshlrev_b32_e32 v115, 16, v150
	v_and_b32_e32 v116, 0xffff0000, v150
	v_mul_f32_e32 v114, 0x3fd744fd, v193
	v_sub_f32_e32 v117, v116, v192
	v_sub_f32_e32 v116, v115, v192
	v_sub_f32_e32 v118, v118, v192
	v_pk_mul_f32 v[118:119], v[114:115], v[118:119] op_sel_hi:[0,1]
	v_pk_mul_f32 v[116:117], v[114:115], v[116:117] op_sel_hi:[0,1]
	v_lshlrev_b32_e32 v120, 16, v152
	v_and_b32_e32 v121, 0xffff0000, v152
	v_and_b32_e32 v124, 0xffff0000, v153
	v_pk_fma_f32 v[116:117], v[142:143], v[116:117], v[206:207]
	v_pk_fma_f32 v[118:119], v[144:145], v[118:119], v[204:205]
	v_pk_fma_f32 v[110:111], v[110:111], v[138:139], v[116:117]
	v_pk_fma_f32 v[112:113], v[112:113], v[140:141], v[118:119]
	v_sub_f32_e32 v117, v121, v192
	v_sub_f32_e32 v116, v120, v192
	v_sub_f32_e32 v119, v124, v192
	v_sub_f32_e32 v118, v123, v192
	v_pk_mul_f32 v[118:119], v[114:115], v[118:119] op_sel_hi:[0,1]
	v_pk_mul_f32 v[116:117], v[114:115], v[116:117] op_sel_hi:[0,1]
	v_pk_fma_f32 v[116:117], v[134:135], v[116:117], v[202:203]
	v_pk_fma_f32 v[118:119], v[136:137], v[118:119], v[200:201]
	v_lshlrev_b32_e32 v115, 16, v149
	v_pk_fma_f32 v[118:119], v[108:109], v[132:133], v[118:119]
	v_pk_fma_f32 v[108:109], v[106:107], v[130:131], v[116:117]
	v_cvt_pk_bf16_f32 v106, v110, v111
	v_cvt_pk_bf16_f32 v107, v112, v113
	v_lshlrev_b32_e32 v110, 16, v147
	v_cvt_pk_bf16_f32 v108, v108, v109
	v_cvt_pk_bf16_f32 v109, v118, v119
	global_store_dwordx4 v230, v[106:109], s[42:43]
	v_and_b32_e32 v111, 0xffff0000, v147
	v_sub_f32_e32 v111, v111, v190
	v_lshlrev_b32_e32 v107, 16, v146
	v_and_b32_e32 v108, 0xffff0000, v146
	v_mul_f32_e32 v106, 0x3fd744fd, v191
	v_sub_f32_e32 v109, v108, v190
	v_sub_f32_e32 v108, v107, v190
	v_sub_f32_e32 v110, v110, v190
	v_pk_mul_f32 v[110:111], v[106:107], v[110:111] op_sel_hi:[0,1]
	v_pk_mul_f32 v[108:109], v[106:107], v[108:109] op_sel_hi:[0,1]
	v_lshlrev_b32_e32 v112, 16, v148
	v_and_b32_e32 v113, 0xffff0000, v148
	v_and_b32_e32 v116, 0xffff0000, v149
	v_pk_fma_f32 v[108:109], v[142:143], v[108:109], v[206:207]
	v_pk_fma_f32 v[110:111], v[144:145], v[110:111], v[204:205]
	v_pk_fma_f32 v[102:103], v[102:103], v[138:139], v[108:109]
	v_pk_fma_f32 v[104:105], v[104:105], v[140:141], v[110:111]
	v_sub_f32_e32 v109, v113, v190
	v_sub_f32_e32 v108, v112, v190
	v_sub_f32_e32 v111, v116, v190
	v_sub_f32_e32 v110, v115, v190
	v_pk_mul_f32 v[110:111], v[106:107], v[110:111] op_sel_hi:[0,1]
	v_pk_mul_f32 v[108:109], v[106:107], v[108:109] op_sel_hi:[0,1]
	v_pk_fma_f32 v[108:109], v[134:135], v[108:109], v[202:203]
	v_pk_fma_f32 v[110:111], v[136:137], v[110:111], v[200:201]
	v_add_u32_e32 v107, 0xb0000, v228
	v_pk_fma_f32 v[110:111], v[100:101], v[132:133], v[110:111]
	v_pk_fma_f32 v[100:101], v[98:99], v[130:131], v[108:109]
	v_cvt_pk_bf16_f32 v98, v102, v103
	v_cvt_pk_bf16_f32 v99, v104, v105
	v_add_u32_e32 v104, 0x90000, v228
	v_cvt_pk_bf16_f32 v100, v100, v101
	v_cvt_pk_bf16_f32 v101, v110, v111
	global_store_dwordx4 v229, v[98:101], s[42:43]
	v_add_u32_e32 v105, 0xa0000, v228
	s_nop 0
	v_add_u32_e32 v99, 0x80000, v228
	s_nop 0
	s_nop 0
	s_nop 0
	s_waitcnt vmcnt(6)
	v_mul_f32_e32 v98, 0x3fd744fd, v189
	v_lshlrev_b32_e32 v112, 16, v234
	v_and_b32_e32 v100, 0xffff0000, v234
	v_lshlrev_b32_e32 v113, 16, v235
	v_and_b32_e32 v115, 0xffff0000, v235
	v_lshlrev_b32_e32 v120, 16, v236
	v_and_b32_e32 v121, 0xffff0000, v236
	v_lshlrev_b32_e32 v123, 16, v237
	v_and_b32_e32 v128, 0xffff0000, v237
	v_sub_f32_e32 v101, v100, v188
	v_sub_f32_e32 v100, v112, v188
	v_sub_f32_e32 v103, v115, v188
	v_sub_f32_e32 v102, v113, v188
	v_pk_mul_f32 v[102:103], v[98:99], v[102:103] op_sel_hi:[0,1]
	v_pk_mul_f32 v[100:101], v[98:99], v[100:101] op_sel_hi:[0,1]
	v_pk_fma_f32 v[100:101], v[142:143], v[100:101], v[206:207]
	v_pk_fma_f32 v[102:103], v[144:145], v[102:103], v[204:205]
	v_pk_fma_f32 v[94:95], v[94:95], v[138:139], v[100:101]
	v_pk_fma_f32 v[96:97], v[96:97], v[140:141], v[102:103]
	v_sub_f32_e32 v101, v121, v188
	v_sub_f32_e32 v100, v120, v188
	v_sub_f32_e32 v103, v128, v188
	v_sub_f32_e32 v102, v123, v188
	v_pk_mul_f32 v[102:103], v[98:99], v[102:103] op_sel_hi:[0,1]
	v_pk_mul_f32 v[100:101], v[98:99], v[100:101] op_sel_hi:[0,1]
	v_pk_fma_f32 v[100:101], v[134:135], v[100:101], v[202:203]
	v_pk_fma_f32 v[102:103], v[136:137], v[102:103], v[200:201]
	s_waitcnt vmcnt(5)
	s_waitcnt vmcnt(4)
	v_pk_fma_f32 v[102:103], v[92:93], v[132:133], v[102:103]
	v_pk_fma_f32 v[92:93], v[90:91], v[130:131], v[100:101]
	v_cvt_pk_bf16_f32 v90, v94, v95
	v_cvt_pk_bf16_f32 v91, v96, v97
	v_lshlrev_b32_e32 v94, 16, v239
	v_cvt_pk_bf16_f32 v92, v92, v93
	v_cvt_pk_bf16_f32 v93, v102, v103
	global_store_dwordx4 v99, v[90:93], s[42:43]
	v_and_b32_e32 v95, 0xffff0000, v239
	v_sub_f32_e32 v95, v95, v186
	v_lshlrev_b32_e32 v91, 16, v238
	v_and_b32_e32 v92, 0xffff0000, v238
	v_mul_f32_e32 v90, 0x3fd744fd, v187
	v_sub_f32_e32 v93, v92, v186
	v_sub_f32_e32 v92, v91, v186
	v_sub_f32_e32 v94, v94, v186
	v_pk_mul_f32 v[94:95], v[90:91], v[94:95] op_sel_hi:[0,1]
	v_pk_mul_f32 v[92:93], v[90:91], v[92:93] op_sel_hi:[0,1]
	v_lshlrev_b32_e32 v96, 16, v240
	v_and_b32_e32 v97, 0xffff0000, v240
	v_lshlrev_b32_e32 v99, 16, v241
	v_and_b32_e32 v100, 0xffff0000, v241
	v_pk_fma_f32 v[92:93], v[142:143], v[92:93], v[206:207]
	v_pk_fma_f32 v[94:95], v[144:145], v[94:95], v[204:205]
	v_pk_fma_f32 v[86:87], v[86:87], v[138:139], v[92:93]
	v_pk_fma_f32 v[88:89], v[88:89], v[140:141], v[94:95]
	v_sub_f32_e32 v93, v97, v186
	v_sub_f32_e32 v92, v96, v186
	v_sub_f32_e32 v95, v100, v186
	v_sub_f32_e32 v94, v99, v186
	v_pk_mul_f32 v[94:95], v[90:91], v[94:95] op_sel_hi:[0,1]
	v_pk_mul_f32 v[92:93], v[90:91], v[92:93] op_sel_hi:[0,1]
	v_pk_fma_f32 v[92:93], v[134:135], v[92:93], v[202:203]
	v_pk_fma_f32 v[94:95], v[136:137], v[94:95], v[200:201]
	v_lshlrev_b32_e32 v91, 16, v245
	v_pk_fma_f32 v[94:95], v[84:85], v[132:133], v[94:95]
	v_pk_fma_f32 v[84:85], v[82:83], v[130:131], v[92:93]
	v_cvt_pk_bf16_f32 v82, v86, v87
	v_cvt_pk_bf16_f32 v83, v88, v89
	v_lshlrev_b32_e32 v86, 16, v243
	v_cvt_pk_bf16_f32 v84, v84, v85
	v_cvt_pk_bf16_f32 v85, v94, v95
	global_store_dwordx4 v104, v[82:85], s[42:43]
	v_and_b32_e32 v87, 0xffff0000, v243
	v_sub_f32_e32 v87, v87, v184
	v_lshlrev_b32_e32 v83, 16, v242
	v_and_b32_e32 v84, 0xffff0000, v242
	v_mul_f32_e32 v82, 0x3fd744fd, v185
	v_sub_f32_e32 v85, v84, v184
	v_sub_f32_e32 v84, v83, v184
	v_sub_f32_e32 v86, v86, v184
	v_pk_mul_f32 v[86:87], v[82:83], v[86:87] op_sel_hi:[0,1]
	v_pk_mul_f32 v[84:85], v[82:83], v[84:85] op_sel_hi:[0,1]
	v_lshlrev_b32_e32 v88, 16, v244
	v_and_b32_e32 v89, 0xffff0000, v244
	v_and_b32_e32 v92, 0xffff0000, v245
	v_pk_fma_f32 v[84:85], v[142:143], v[84:85], v[206:207]
	v_pk_fma_f32 v[86:87], v[144:145], v[86:87], v[204:205]
	v_pk_fma_f32 v[78:79], v[78:79], v[138:139], v[84:85]
	v_pk_fma_f32 v[80:81], v[80:81], v[140:141], v[86:87]
	v_sub_f32_e32 v85, v89, v184
	v_sub_f32_e32 v84, v88, v184
	v_sub_f32_e32 v87, v92, v184
	v_sub_f32_e32 v86, v91, v184
	v_pk_mul_f32 v[86:87], v[82:83], v[86:87] op_sel_hi:[0,1]
	v_pk_mul_f32 v[84:85], v[82:83], v[84:85] op_sel_hi:[0,1]
	v_pk_fma_f32 v[84:85], v[134:135], v[84:85], v[202:203]
	v_pk_fma_f32 v[86:87], v[136:137], v[86:87], v[200:201]
	v_add_u32_e32 v83, 0x80, v227
	v_pk_fma_f32 v[86:87], v[76:77], v[132:133], v[86:87]
	v_pk_fma_f32 v[76:77], v[74:75], v[130:131], v[84:85]
	v_cvt_pk_bf16_f32 v74, v78, v79
	v_cvt_pk_bf16_f32 v75, v80, v81
	v_mul_f32_e32 v84, 0x3fd744fd, v183
	v_cvt_pk_bf16_f32 v76, v76, v77
	v_cvt_pk_bf16_f32 v77, v86, v87
	global_store_dwordx4 v105, v[74:77], s[42:43]
	v_lshlrev_b32_e32 v78, 16, v176
	v_and_b32_e32 v79, 0xffff0000, v176
	v_lshlrev_b32_e32 v74, 16, v174
	v_and_b32_e32 v75, 0xffff0000, v174
	v_lshlrev_b32_e32 v76, 16, v175
	v_and_b32_e32 v77, 0xffff0000, v175
	v_sub_f32_e32 v75, v75, v182
	v_sub_f32_e32 v74, v74, v182
	v_sub_f32_e32 v77, v77, v182
	v_sub_f32_e32 v76, v76, v182
	v_pk_mul_f32 v[76:77], v[84:85], v[76:77] op_sel_hi:[0,1]
	v_pk_mul_f32 v[74:75], v[84:85], v[74:75] op_sel_hi:[0,1]
	v_lshlrev_b32_e32 v80, 16, v177
	v_and_b32_e32 v81, 0xffff0000, v177
	v_pk_fma_f32 v[74:75], v[142:143], v[74:75], v[206:207]
	v_pk_fma_f32 v[76:77], v[144:145], v[76:77], v[204:205]
	v_pk_fma_f32 v[70:71], v[70:71], v[138:139], v[74:75]
	v_pk_fma_f32 v[72:73], v[72:73], v[140:141], v[76:77]
	v_sub_f32_e32 v75, v79, v182
	v_sub_f32_e32 v74, v78, v182
	v_sub_f32_e32 v77, v81, v182
	v_sub_f32_e32 v76, v80, v182
	v_pk_mul_f32 v[76:77], v[84:85], v[76:77] op_sel_hi:[0,1]
	v_pk_mul_f32 v[74:75], v[84:85], v[74:75] op_sel_hi:[0,1]
	v_pk_fma_f32 v[74:75], v[134:135], v[74:75], v[202:203]
	v_pk_fma_f32 v[76:77], v[136:137], v[76:77], v[200:201]
	v_lshlrev_b32_e32 v85, 2, v83
	v_pk_fma_f32 v[76:77], v[68:69], v[132:133], v[76:77]
	v_pk_fma_f32 v[68:69], v[66:67], v[130:131], v[74:75]
	v_cvt_pk_bf16_f32 v66, v70, v71
	v_cvt_pk_bf16_f32 v67, v72, v73
	v_lshl_add_u32 v83, v83, 1, v226
	v_cvt_pk_bf16_f32 v68, v68, v69
	v_cvt_pk_bf16_f32 v69, v76, v77
	global_store_dwordx4 v107, v[66:69], s[42:43]
	global_load_dwordx4 v[66:69], v85, s[20:21] offset:16
	s_nop 0
	global_load_dwordx4 v[74:77], v85, s[20:21]
	global_load_dwordx4 v[70:73], v85, s[4:5] offset:16
	global_load_dwordx4 v[78:81], v85, s[4:5]
	global_load_dwordx4 v[100:103], v85, s[0:1] offset:16
	global_load_dwordx4 v[86:89], v85, s[0:1]
	v_add_u32_e32 v85, 0x10000, v83
	v_add_u32_e32 v91, 0x20000, v83
	v_add_u32_e32 v99, 0x30000, v83
	global_load_dwordx4 v[108:111], v85, s[46:47]
	global_load_dwordx4 v[116:119], v91, s[46:47]
	global_load_dwordx4 v[124:127], v99, s[46:47]
	s_mov_b64 s[20:21], -1
	s_waitcnt vmcnt(3)
	v_pk_mul_f32 v[92:93], v[88:89], s[76:77] op_sel_hi:[1,0]
	v_pk_mul_f32 v[94:95], v[86:87], s[76:77] op_sel_hi:[1,0]
	v_pk_mul_f32 v[86:87], v[102:103], s[76:77] op_sel_hi:[1,0]
	v_pk_mul_f32 v[88:89], v[100:101], s[76:77] op_sel_hi:[1,0]
	global_load_dwordx4 v[100:103], v83, s[46:47]
	v_add_u32_e32 v246, 0x80000, v83
	global_load_dwordx4 v[234:237], v246, s[46:47]
	v_add_u32_e32 v246, 0x90000, v83
	global_load_dwordx4 v[238:241], v246, s[46:47]
	v_add_u32_e32 v246, 0xa0000, v83
	global_load_dwordx4 v[242:245], v246, s[46:47]
	v_add_u32_e32 v246, 0xb0000, v83
	global_load_dwordx4 v[174:177], v246, s[46:47]
	s_waitcnt vmcnt(4)
	s_nop 0
	v_lshlrev_b32_e32 v96, 16, v100
	v_and_b32_e32 v97, 0xffff0000, v100
	v_lshlrev_b32_e32 v100, 16, v101
	v_and_b32_e32 v101, 0xffff0000, v101
	v_sub_f32_e32 v97, v97, v196
	v_sub_f32_e32 v96, v96, v196
	v_sub_f32_e32 v101, v101, v196
	v_sub_f32_e32 v100, v100, v196
	v_pk_mul_f32 v[100:101], v[198:199], v[100:101] op_sel_hi:[0,1]
	v_pk_mul_f32 v[96:97], v[198:199], v[96:97] op_sel_hi:[0,1]
	v_lshlrev_b32_e32 v104, 16, v102
	v_and_b32_e32 v102, 0xffff0000, v102
	v_lshlrev_b32_e32 v105, 16, v103
	v_and_b32_e32 v103, 0xffff0000, v103
	v_pk_fma_f32 v[96:97], v[78:79], v[96:97], v[94:95]
	v_pk_fma_f32 v[100:101], v[80:81], v[100:101], v[92:93]
	v_pk_fma_f32 v[60:61], v[60:61], v[74:75], v[96:97]
	v_pk_fma_f32 v[62:63], v[62:63], v[76:77], v[100:101]
	v_sub_f32_e32 v97, v102, v196
	v_sub_f32_e32 v96, v104, v196
	v_sub_f32_e32 v101, v103, v196
	v_sub_f32_e32 v100, v105, v196
	v_pk_mul_f32 v[100:101], v[198:199], v[100:101] op_sel_hi:[0,1]
	v_pk_mul_f32 v[96:97], v[198:199], v[96:97] op_sel_hi:[0,1]
	v_pk_fma_f32 v[96:97], v[70:71], v[96:97], v[88:89]
	v_pk_fma_f32 v[100:101], v[72:73], v[100:101], v[86:87]
	s_nop 0
	v_pk_fma_f32 v[100:101], v[58:59], v[68:69], v[100:101]
	v_pk_fma_f32 v[58:59], v[56:57], v[66:67], v[96:97]
	v_cvt_pk_bf16_f32 v56, v60, v61
	v_cvt_pk_bf16_f32 v57, v62, v63
	v_lshlrev_b32_e32 v60, 16, v110
	v_cvt_pk_bf16_f32 v58, v58, v59
	v_cvt_pk_bf16_f32 v59, v100, v101
	global_store_dwordx4 v83, v[56:59], s[42:43]
	v_and_b32_e32 v61, 0xffff0000, v110
	v_lshlrev_b32_e32 v62, 16, v111
	v_lshlrev_b32_e32 v56, 16, v108
	v_and_b32_e32 v57, 0xffff0000, v108
	v_lshlrev_b32_e32 v58, 16, v109
	v_and_b32_e32 v59, 0xffff0000, v109
	v_sub_f32_e32 v57, v57, v194
	v_sub_f32_e32 v56, v56, v194
	v_sub_f32_e32 v59, v59, v194
	v_sub_f32_e32 v58, v58, v194
	v_pk_mul_f32 v[58:59], v[122:123], v[58:59] op_sel_hi:[0,1]
	v_pk_mul_f32 v[56:57], v[122:123], v[56:57] op_sel_hi:[0,1]
	v_and_b32_e32 v63, 0xffff0000, v111
	v_pk_fma_f32 v[56:57], v[78:79], v[56:57], v[94:95]
	v_pk_fma_f32 v[58:59], v[80:81], v[58:59], v[92:93]
	v_pk_fma_f32 v[52:53], v[52:53], v[74:75], v[56:57]
	v_pk_fma_f32 v[54:55], v[54:55], v[76:77], v[58:59]
	v_sub_f32_e32 v57, v61, v194
	v_sub_f32_e32 v56, v60, v194
	v_sub_f32_e32 v59, v63, v194
	v_sub_f32_e32 v58, v62, v194
	v_pk_mul_f32 v[58:59], v[122:123], v[58:59] op_sel_hi:[0,1]
	v_pk_mul_f32 v[56:57], v[122:123], v[56:57] op_sel_hi:[0,1]
	v_pk_fma_f32 v[56:57], v[70:71], v[56:57], v[88:89]
	v_pk_fma_f32 v[58:59], v[72:73], v[58:59], v[86:87]
	s_nop 0
	v_pk_fma_f32 v[58:59], v[50:51], v[68:69], v[58:59]
	v_pk_fma_f32 v[50:51], v[48:49], v[66:67], v[56:57]
	v_cvt_pk_bf16_f32 v48, v52, v53
	v_cvt_pk_bf16_f32 v49, v54, v55
	v_lshlrev_b32_e32 v52, 16, v118
	v_cvt_pk_bf16_f32 v50, v50, v51
	v_cvt_pk_bf16_f32 v51, v58, v59
	global_store_dwordx4 v85, v[48:51], s[42:43]
	v_and_b32_e32 v53, 0xffff0000, v118
	v_lshlrev_b32_e32 v54, 16, v119
	v_lshlrev_b32_e32 v48, 16, v116
	v_and_b32_e32 v49, 0xffff0000, v116
	v_lshlrev_b32_e32 v50, 16, v117
	v_and_b32_e32 v51, 0xffff0000, v117
	v_sub_f32_e32 v49, v49, v192
	v_sub_f32_e32 v48, v48, v192
	v_sub_f32_e32 v51, v51, v192
	v_sub_f32_e32 v50, v50, v192
	v_pk_mul_f32 v[50:51], v[114:115], v[50:51] op_sel_hi:[0,1]
	v_pk_mul_f32 v[48:49], v[114:115], v[48:49] op_sel_hi:[0,1]
	v_and_b32_e32 v55, 0xffff0000, v119
	v_pk_fma_f32 v[48:49], v[78:79], v[48:49], v[94:95]
	v_pk_fma_f32 v[50:51], v[80:81], v[50:51], v[92:93]
	v_pk_fma_f32 v[44:45], v[44:45], v[74:75], v[48:49]
	v_pk_fma_f32 v[46:47], v[46:47], v[76:77], v[50:51]
	v_sub_f32_e32 v49, v53, v192
	v_sub_f32_e32 v48, v52, v192
	v_sub_f32_e32 v51, v55, v192
	v_sub_f32_e32 v50, v54, v192
	v_pk_mul_f32 v[50:51], v[114:115], v[50:51] op_sel_hi:[0,1]
	v_pk_mul_f32 v[48:49], v[114:115], v[48:49] op_sel_hi:[0,1]
	v_pk_fma_f32 v[48:49], v[70:71], v[48:49], v[88:89]
	v_pk_fma_f32 v[50:51], v[72:73], v[50:51], v[86:87]
	s_nop 0
	v_pk_fma_f32 v[50:51], v[42:43], v[68:69], v[50:51]
	v_pk_fma_f32 v[42:43], v[40:41], v[66:67], v[48:49]
	v_cvt_pk_bf16_f32 v40, v44, v45
	v_cvt_pk_bf16_f32 v41, v46, v47
	v_lshlrev_b32_e32 v44, 16, v126
	v_cvt_pk_bf16_f32 v42, v42, v43
	v_cvt_pk_bf16_f32 v43, v50, v51
	global_store_dwordx4 v91, v[40:43], s[42:43]
	v_and_b32_e32 v45, 0xffff0000, v126
	v_lshlrev_b32_e32 v46, 16, v127
	v_lshlrev_b32_e32 v40, 16, v124
	v_and_b32_e32 v41, 0xffff0000, v124
	v_lshlrev_b32_e32 v42, 16, v125
	v_and_b32_e32 v43, 0xffff0000, v125
	v_sub_f32_e32 v41, v41, v190
	v_sub_f32_e32 v40, v40, v190
	v_sub_f32_e32 v43, v43, v190
	v_sub_f32_e32 v42, v42, v190
	v_pk_mul_f32 v[42:43], v[106:107], v[42:43] op_sel_hi:[0,1]
	v_pk_mul_f32 v[40:41], v[106:107], v[40:41] op_sel_hi:[0,1]
	v_and_b32_e32 v47, 0xffff0000, v127
	v_pk_fma_f32 v[40:41], v[78:79], v[40:41], v[94:95]
	v_pk_fma_f32 v[42:43], v[80:81], v[42:43], v[92:93]
	v_pk_fma_f32 v[36:37], v[36:37], v[74:75], v[40:41]
	v_pk_fma_f32 v[38:39], v[38:39], v[76:77], v[42:43]
	v_sub_f32_e32 v41, v45, v190
	v_sub_f32_e32 v40, v44, v190
	v_sub_f32_e32 v43, v47, v190
	v_sub_f32_e32 v42, v46, v190
	v_pk_mul_f32 v[42:43], v[106:107], v[42:43] op_sel_hi:[0,1]
	v_pk_mul_f32 v[40:41], v[106:107], v[40:41] op_sel_hi:[0,1]
	v_pk_fma_f32 v[40:41], v[70:71], v[40:41], v[88:89]
	v_pk_fma_f32 v[42:43], v[72:73], v[42:43], v[86:87]
	v_add_u32_e32 v48, 0x80000, v83
	v_pk_fma_f32 v[42:43], v[34:35], v[68:69], v[42:43]
	v_pk_fma_f32 v[34:35], v[32:33], v[66:67], v[40:41]
	v_cvt_pk_bf16_f32 v32, v36, v37
	v_cvt_pk_bf16_f32 v33, v38, v39
	v_add_u32_e32 v49, 0x90000, v83
	v_cvt_pk_bf16_f32 v34, v34, v35
	v_cvt_pk_bf16_f32 v35, v42, v43
	global_store_dwordx4 v99, v[32:35], s[42:43]
	s_nop 0
	v_add_u32_e32 v50, 0xa0000, v83
	v_add_u32_e32 v51, 0xb0000, v83
	s_nop 0
	s_nop 0
	s_nop 0
	s_waitcnt vmcnt(7)
	s_waitcnt vmcnt(6)
	s_waitcnt vmcnt(5)
	s_waitcnt vmcnt(4)
	v_lshlrev_b32_e32 v52, 16, v234
	v_and_b32_e32 v32, 0xffff0000, v234
	v_lshlrev_b32_e32 v53, 16, v235
	v_and_b32_e32 v54, 0xffff0000, v235
	v_lshlrev_b32_e32 v55, 16, v236
	v_and_b32_e32 v56, 0xffff0000, v236
	v_lshlrev_b32_e32 v57, 16, v237
	v_and_b32_e32 v58, 0xffff0000, v237
	v_sub_f32_e32 v33, v32, v188
	v_sub_f32_e32 v32, v52, v188
	v_sub_f32_e32 v35, v54, v188
	v_sub_f32_e32 v34, v53, v188
	v_pk_mul_f32 v[34:35], v[98:99], v[34:35] op_sel_hi:[0,1]
	v_pk_mul_f32 v[32:33], v[98:99], v[32:33] op_sel_hi:[0,1]
	v_pk_fma_f32 v[32:33], v[78:79], v[32:33], v[94:95]
	v_pk_fma_f32 v[34:35], v[80:81], v[34:35], v[92:93]
	v_pk_fma_f32 v[28:29], v[28:29], v[74:75], v[32:33]
	v_pk_fma_f32 v[30:31], v[30:31], v[76:77], v[34:35]
	v_sub_f32_e32 v33, v56, v188
	v_sub_f32_e32 v32, v55, v188
	v_sub_f32_e32 v35, v58, v188
	v_sub_f32_e32 v34, v57, v188
	v_pk_mul_f32 v[34:35], v[98:99], v[34:35] op_sel_hi:[0,1]
	v_pk_mul_f32 v[32:33], v[98:99], v[32:33] op_sel_hi:[0,1]
	v_pk_fma_f32 v[32:33], v[70:71], v[32:33], v[88:89]
	v_pk_fma_f32 v[34:35], v[72:73], v[34:35], v[86:87]
	s_nop 0
	v_pk_fma_f32 v[34:35], v[26:27], v[68:69], v[34:35]
	v_pk_fma_f32 v[26:27], v[24:25], v[66:67], v[32:33]
	v_cvt_pk_bf16_f32 v24, v28, v29
	v_cvt_pk_bf16_f32 v25, v30, v31
	v_lshlrev_b32_e32 v28, 16, v240
	v_cvt_pk_bf16_f32 v26, v26, v27
	v_cvt_pk_bf16_f32 v27, v34, v35
	global_store_dwordx4 v48, v[24:27], s[42:43]
	v_and_b32_e32 v29, 0xffff0000, v240
	v_lshlrev_b32_e32 v30, 16, v241
	v_lshlrev_b32_e32 v24, 16, v238
	v_and_b32_e32 v25, 0xffff0000, v238
	v_lshlrev_b32_e32 v26, 16, v239
	v_and_b32_e32 v27, 0xffff0000, v239
	v_sub_f32_e32 v25, v25, v186
	v_sub_f32_e32 v24, v24, v186
	v_sub_f32_e32 v27, v27, v186
	v_sub_f32_e32 v26, v26, v186
	v_pk_mul_f32 v[26:27], v[90:91], v[26:27] op_sel_hi:[0,1]
	v_pk_mul_f32 v[24:25], v[90:91], v[24:25] op_sel_hi:[0,1]
	v_and_b32_e32 v31, 0xffff0000, v241
	v_pk_fma_f32 v[24:25], v[78:79], v[24:25], v[94:95]
	v_pk_fma_f32 v[26:27], v[80:81], v[26:27], v[92:93]
	v_pk_fma_f32 v[20:21], v[20:21], v[74:75], v[24:25]
	v_pk_fma_f32 v[22:23], v[22:23], v[76:77], v[26:27]
	v_sub_f32_e32 v25, v29, v186
	v_sub_f32_e32 v24, v28, v186
	v_sub_f32_e32 v27, v31, v186
	v_sub_f32_e32 v26, v30, v186
	v_pk_mul_f32 v[26:27], v[90:91], v[26:27] op_sel_hi:[0,1]
	v_pk_mul_f32 v[24:25], v[90:91], v[24:25] op_sel_hi:[0,1]
	v_pk_fma_f32 v[24:25], v[70:71], v[24:25], v[88:89]
	v_pk_fma_f32 v[26:27], v[72:73], v[26:27], v[86:87]
	s_nop 0
	v_pk_fma_f32 v[26:27], v[18:19], v[68:69], v[26:27]
	v_pk_fma_f32 v[18:19], v[16:17], v[66:67], v[24:25]
	v_cvt_pk_bf16_f32 v16, v20, v21
	v_cvt_pk_bf16_f32 v17, v22, v23
	v_lshlrev_b32_e32 v20, 16, v244
	v_cvt_pk_bf16_f32 v18, v18, v19
	v_cvt_pk_bf16_f32 v19, v26, v27
	global_store_dwordx4 v49, v[16:19], s[42:43]
	v_and_b32_e32 v21, 0xffff0000, v244
	v_lshlrev_b32_e32 v22, 16, v245
	v_lshlrev_b32_e32 v16, 16, v242
	v_and_b32_e32 v17, 0xffff0000, v242
	v_lshlrev_b32_e32 v18, 16, v243
	v_and_b32_e32 v19, 0xffff0000, v243
	v_sub_f32_e32 v17, v17, v184
	v_sub_f32_e32 v16, v16, v184
	v_sub_f32_e32 v19, v19, v184
	v_sub_f32_e32 v18, v18, v184
	v_pk_mul_f32 v[18:19], v[82:83], v[18:19] op_sel_hi:[0,1]
	v_pk_mul_f32 v[16:17], v[82:83], v[16:17] op_sel_hi:[0,1]
	v_and_b32_e32 v23, 0xffff0000, v245
	v_pk_fma_f32 v[16:17], v[78:79], v[16:17], v[94:95]
	v_pk_fma_f32 v[18:19], v[80:81], v[18:19], v[92:93]
	v_pk_fma_f32 v[12:13], v[12:13], v[74:75], v[16:17]
	v_pk_fma_f32 v[14:15], v[14:15], v[76:77], v[18:19]
	v_sub_f32_e32 v17, v21, v184
	v_sub_f32_e32 v16, v20, v184
	v_sub_f32_e32 v19, v23, v184
	v_sub_f32_e32 v18, v22, v184
	v_pk_mul_f32 v[18:19], v[82:83], v[18:19] op_sel_hi:[0,1]
	v_pk_mul_f32 v[16:17], v[82:83], v[16:17] op_sel_hi:[0,1]
	v_pk_fma_f32 v[16:17], v[70:71], v[16:17], v[88:89]
	v_pk_fma_f32 v[18:19], v[72:73], v[18:19], v[86:87]
	s_nop 0
	v_pk_fma_f32 v[18:19], v[10:11], v[68:69], v[18:19]
	v_pk_fma_f32 v[10:11], v[8:9], v[66:67], v[16:17]
	v_cvt_pk_bf16_f32 v8, v12, v13
	v_cvt_pk_bf16_f32 v9, v14, v15
	v_lshlrev_b32_e32 v12, 16, v176
	v_cvt_pk_bf16_f32 v10, v10, v11
	v_cvt_pk_bf16_f32 v11, v18, v19
	global_store_dwordx4 v50, v[8:11], s[42:43]
	v_and_b32_e32 v13, 0xffff0000, v176
	v_lshlrev_b32_e32 v14, 16, v177
	v_lshlrev_b32_e32 v8, 16, v174
	v_and_b32_e32 v9, 0xffff0000, v174
	v_lshlrev_b32_e32 v10, 16, v175
	v_and_b32_e32 v11, 0xffff0000, v175
	v_sub_f32_e32 v9, v9, v182
	v_sub_f32_e32 v8, v8, v182
	v_sub_f32_e32 v11, v11, v182
	v_sub_f32_e32 v10, v10, v182
	v_pk_mul_f32 v[10:11], v[84:85], v[10:11] op_sel_hi:[0,1]
	v_pk_mul_f32 v[8:9], v[84:85], v[8:9] op_sel_hi:[0,1]
	v_and_b32_e32 v15, 0xffff0000, v177
	v_pk_fma_f32 v[8:9], v[78:79], v[8:9], v[94:95]
	v_pk_fma_f32 v[10:11], v[80:81], v[10:11], v[92:93]
	v_pk_fma_f32 v[4:5], v[4:5], v[74:75], v[8:9]
	v_pk_fma_f32 v[6:7], v[6:7], v[76:77], v[10:11]
	v_sub_f32_e32 v9, v13, v182
	v_sub_f32_e32 v8, v12, v182
	v_sub_f32_e32 v11, v15, v182
	v_sub_f32_e32 v10, v14, v182
	v_pk_mul_f32 v[10:11], v[84:85], v[10:11] op_sel_hi:[0,1]
	v_pk_mul_f32 v[8:9], v[84:85], v[8:9] op_sel_hi:[0,1]
	v_pk_fma_f32 v[8:9], v[70:71], v[8:9], v[88:89]
	v_pk_fma_f32 v[10:11], v[72:73], v[10:11], v[86:87]
	s_nop 0
	v_pk_fma_f32 v[10:11], v[2:3], v[68:69], v[10:11]
	v_pk_fma_f32 v[2:3], v[0:1], v[66:67], v[8:9]
	v_cvt_pk_bf16_f32 v0, v4, v5
	v_cvt_pk_bf16_f32 v1, v6, v7
	s_nop 0
	v_cvt_pk_bf16_f32 v2, v2, v3
	v_cvt_pk_bf16_f32 v3, v10, v11
	global_store_dwordx4 v51, v[0:3], s[42:43]
	s_cbranch_vccnz .LBB0_1315
	s_andn2_b64 vcc, exec, s[8:9]
	s_cbranch_vccnz .LBB0_1314
	s_barrier
	s_branch .LBB0_1314
